# prologue phase (mod GEMV): k-loop unrolled x8 with an 8-deep register ring so 32 weight loads are in flight per thread instead of 4; plus hgB LDS-DMA and GEMM boundary trims
# speedup vs baseline: 1.0164x; 1.0020x over previous
.LBB0_418:
	v_lshl_add_u64 v[20:21], v[6:7], 0, s[6:7]
	v_add_co_u32_e32 v22, vcc, s84, v20
	global_load_dword v68, v[20:21], off nt
	s_nop 0
	v_addc_co_u32_e32 v23, vcc, 0, v21, vcc
	v_add_co_u32_e32 v24, vcc, s33, v20
	s_mov_b32 s13, 0x12000
	s_nop 0
	v_addc_co_u32_e32 v25, vcc, 0, v21, vcc
	v_add_co_u32_e32 v20, vcc, s13, v20
	s_add_u32 s6, s6, 0x18000
	s_addc_u32 s7, s7, 0
	v_addc_co_u32_e32 v21, vcc, 0, v21, vcc
	global_load_dword v70, v[22:23], off nt
	global_load_dword v72, v[24:25], off nt
	global_load_dword v74, v[20:21], off nt
	v_lshl_add_u64 v[20:21], v[6:7], 0, s[6:7]
	v_add_co_u32_e32 v22, vcc, s84, v20
	global_load_dword v76, v[20:21], off nt
	s_nop 0
	v_addc_co_u32_e32 v23, vcc, 0, v21, vcc
	v_add_co_u32_e32 v24, vcc, s33, v20
	s_mov_b32 s13, 0x12000
	s_nop 0
	v_addc_co_u32_e32 v25, vcc, 0, v21, vcc
	v_add_co_u32_e32 v20, vcc, s13, v20
	s_add_u32 s6, s6, 0x18000
	s_addc_u32 s7, s7, 0
	v_addc_co_u32_e32 v21, vcc, 0, v21, vcc
	global_load_dword v78, v[22:23], off nt
	global_load_dword v80, v[24:25], off nt
	global_load_dword v82, v[20:21], off nt
	v_lshl_add_u64 v[20:21], v[6:7], 0, s[6:7]
	v_add_co_u32_e32 v22, vcc, s84, v20
	global_load_dword v84, v[20:21], off nt
	s_nop 0
	v_addc_co_u32_e32 v23, vcc, 0, v21, vcc
	v_add_co_u32_e32 v24, vcc, s33, v20
	s_mov_b32 s13, 0x12000
	s_nop 0
	v_addc_co_u32_e32 v25, vcc, 0, v21, vcc
	v_add_co_u32_e32 v20, vcc, s13, v20
	s_add_u32 s6, s6, 0x18000
	s_addc_u32 s7, s7, 0
	v_addc_co_u32_e32 v21, vcc, 0, v21, vcc
	global_load_dword v86, v[22:23], off nt
	global_load_dword v88, v[24:25], off nt
	global_load_dword v90, v[20:21], off nt
	v_lshl_add_u64 v[20:21], v[6:7], 0, s[6:7]
	v_add_co_u32_e32 v22, vcc, s84, v20
	global_load_dword v92, v[20:21], off nt
	s_nop 0
	v_addc_co_u32_e32 v23, vcc, 0, v21, vcc
	v_add_co_u32_e32 v24, vcc, s33, v20
	s_mov_b32 s13, 0x12000
	s_nop 0
	v_addc_co_u32_e32 v25, vcc, 0, v21, vcc
	v_add_co_u32_e32 v20, vcc, s13, v20
	s_add_u32 s6, s6, 0x18000
	s_addc_u32 s7, s7, 0
	v_addc_co_u32_e32 v21, vcc, 0, v21, vcc
	global_load_dword v94, v[22:23], off nt
	global_load_dword v96, v[24:25], off nt
	global_load_dword v98, v[20:21], off nt
	v_lshl_add_u64 v[20:21], v[6:7], 0, s[6:7]
	v_add_co_u32_e32 v22, vcc, s84, v20
	global_load_dword v100, v[20:21], off nt
	s_nop 0
	v_addc_co_u32_e32 v23, vcc, 0, v21, vcc
	v_add_co_u32_e32 v24, vcc, s33, v20
	s_mov_b32 s13, 0x12000
	s_nop 0
	v_addc_co_u32_e32 v25, vcc, 0, v21, vcc
	v_add_co_u32_e32 v20, vcc, s13, v20
	s_add_u32 s6, s6, 0x18000
	s_addc_u32 s7, s7, 0
	v_addc_co_u32_e32 v21, vcc, 0, v21, vcc
	global_load_dword v102, v[22:23], off nt
	global_load_dword v104, v[24:25], off nt
	global_load_dword v106, v[20:21], off nt
	v_lshl_add_u64 v[20:21], v[6:7], 0, s[6:7]
	v_add_co_u32_e32 v22, vcc, s84, v20
	global_load_dword v108, v[20:21], off nt
	s_nop 0
	v_addc_co_u32_e32 v23, vcc, 0, v21, vcc
	v_add_co_u32_e32 v24, vcc, s33, v20
	s_mov_b32 s13, 0x12000
	s_nop 0
	v_addc_co_u32_e32 v25, vcc, 0, v21, vcc
	v_add_co_u32_e32 v20, vcc, s13, v20
	s_add_u32 s6, s6, 0x18000
	s_addc_u32 s7, s7, 0
	v_addc_co_u32_e32 v21, vcc, 0, v21, vcc
	global_load_dword v110, v[22:23], off nt
	global_load_dword v112, v[24:25], off nt
	global_load_dword v114, v[20:21], off nt
	v_lshl_add_u64 v[20:21], v[6:7], 0, s[6:7]
	v_add_co_u32_e32 v22, vcc, s84, v20
	global_load_dword v116, v[20:21], off nt
	s_nop 0
	v_addc_co_u32_e32 v23, vcc, 0, v21, vcc
	v_add_co_u32_e32 v24, vcc, s33, v20
	s_mov_b32 s13, 0x12000
	s_nop 0
	v_addc_co_u32_e32 v25, vcc, 0, v21, vcc
	v_add_co_u32_e32 v20, vcc, s13, v20
	s_add_u32 s6, s6, 0x18000
	s_addc_u32 s7, s7, 0
	v_addc_co_u32_e32 v21, vcc, 0, v21, vcc
	global_load_dword v118, v[22:23], off nt
	global_load_dword v120, v[24:25], off nt
	global_load_dword v122, v[20:21], off nt
	v_lshl_add_u64 v[20:21], v[6:7], 0, s[6:7]
	v_add_co_u32_e32 v22, vcc, s84, v20
	global_load_dword v140, v[20:21], off nt
	s_nop 0
	v_addc_co_u32_e32 v23, vcc, 0, v21, vcc
	v_add_co_u32_e32 v24, vcc, s33, v20
	s_mov_b32 s13, 0x12000
	s_nop 0
	v_addc_co_u32_e32 v25, vcc, 0, v21, vcc
	v_add_co_u32_e32 v20, vcc, s13, v20
	s_add_u32 s6, s6, 0x18000
	s_addc_u32 s7, s7, 0
	v_addc_co_u32_e32 v21, vcc, 0, v21, vcc
	global_load_dword v142, v[22:23], off nt
	global_load_dword v144, v[24:25], off nt
	global_load_dword v146, v[20:21], off nt
	s_mov_b32 s100, 0
.Lph0_loop:
	s_waitcnt vmcnt(28)
	ds_read_b128 v[20:23], v19
	ds_read_b128 v[24:27], v19 offset:4096
	ds_read_b128 v[28:31], v19 offset:8192
	ds_read_b128 v[32:35], v19 offset:12288
	ds_read_b128 v[36:39], v19 offset:16384
	ds_read_b128 v[40:43], v19 offset:20480
	ds_read_b128 v[44:47], v19 offset:24576
	ds_read_b128 v[48:51], v19 offset:28672
	s_waitcnt lgkmcnt(7)
	v_mov_b32_e32 v60, v20
	s_waitcnt lgkmcnt(6)
	v_mov_b32_e32 v61, v24
	s_waitcnt lgkmcnt(5)
	v_mov_b32_e32 v62, v28
	s_waitcnt lgkmcnt(4)
	v_mov_b32_e32 v63, v32
	s_waitcnt lgkmcnt(3)
	v_mov_b32_e32 v64, v36
	s_waitcnt lgkmcnt(2)
	v_mov_b32_e32 v65, v40
	s_waitcnt lgkmcnt(1)
	v_mov_b32_e32 v66, v44
	s_waitcnt lgkmcnt(0)
	v_mov_b32_e32 v67, v48
	v_mov_b32_e32 v24, v21
	v_mov_b32_e32 v32, v29
	v_mov_b32_e32 v40, v37
	v_mov_b32_e32 v48, v45
	v_mov_b32_e32 v20, v22
	v_mov_b32_e32 v21, v26
	v_mov_b32_e32 v28, v30
	v_mov_b32_e32 v29, v34
	v_mov_b32_e32 v36, v38
	v_mov_b32_e32 v37, v42
	v_mov_b32_e32 v44, v46
	v_mov_b32_e32 v45, v50
	v_mov_b32_e32 v26, v23
	v_mov_b32_e32 v34, v31
	v_mov_b32_e32 v42, v39
	v_mov_b32_e32 v50, v47
	v_add_u32_e32 v19, 16, v19
	v_pk_fma_f32 v[10:11], v[68:69], v[60:61], v[10:11] op_sel_hi:[0,1,1]
	v_pk_fma_f32 v[12:13], v[68:69], v[62:63], v[12:13] op_sel_hi:[0,1,1]
	v_pk_fma_f32 v[14:15], v[68:69], v[64:65], v[14:15] op_sel_hi:[0,1,1]
	v_pk_fma_f32 v[8:9], v[68:69], v[66:67], v[8:9] op_sel_hi:[0,1,1]
	v_pk_fma_f32 v[10:11], v[70:71], v[24:25], v[10:11] op_sel_hi:[0,1,1]
	v_pk_fma_f32 v[12:13], v[70:71], v[32:33], v[12:13] op_sel_hi:[0,1,1]
	v_pk_fma_f32 v[14:15], v[70:71], v[40:41], v[14:15] op_sel_hi:[0,1,1]
	v_pk_fma_f32 v[8:9], v[70:71], v[48:49], v[8:9] op_sel_hi:[0,1,1]
	v_pk_fma_f32 v[10:11], v[72:73], v[20:21], v[10:11] op_sel_hi:[0,1,1]
	v_pk_fma_f32 v[12:13], v[72:73], v[28:29], v[12:13] op_sel_hi:[0,1,1]
	v_pk_fma_f32 v[14:15], v[72:73], v[36:37], v[14:15] op_sel_hi:[0,1,1]
	v_pk_fma_f32 v[8:9], v[72:73], v[44:45], v[8:9] op_sel_hi:[0,1,1]
	v_pk_fma_f32 v[10:11], v[74:75], v[26:27], v[10:11] op_sel_hi:[0,1,1]
	v_pk_fma_f32 v[12:13], v[74:75], v[34:35], v[12:13] op_sel_hi:[0,1,1]
	v_pk_fma_f32 v[14:15], v[74:75], v[42:43], v[14:15] op_sel_hi:[0,1,1]
	v_pk_fma_f32 v[8:9], v[74:75], v[50:51], v[8:9] op_sel_hi:[0,1,1]
	v_lshl_add_u64 v[20:21], v[6:7], 0, s[6:7]
	v_add_co_u32_e32 v22, vcc, s84, v20
	global_load_dword v68, v[20:21], off nt
	s_nop 0
	v_addc_co_u32_e32 v23, vcc, 0, v21, vcc
	v_add_co_u32_e32 v24, vcc, s33, v20
	s_mov_b32 s13, 0x12000
	s_nop 0
	v_addc_co_u32_e32 v25, vcc, 0, v21, vcc
	v_add_co_u32_e32 v20, vcc, s13, v20
	s_add_u32 s6, s6, 0x18000
	s_addc_u32 s7, s7, 0
	v_addc_co_u32_e32 v21, vcc, 0, v21, vcc
	global_load_dword v70, v[22:23], off nt
	global_load_dword v72, v[24:25], off nt
	global_load_dword v74, v[20:21], off nt
	s_waitcnt vmcnt(28)
	ds_read_b128 v[20:23], v19
	ds_read_b128 v[24:27], v19 offset:4096
	ds_read_b128 v[28:31], v19 offset:8192
	ds_read_b128 v[32:35], v19 offset:12288
	ds_read_b128 v[36:39], v19 offset:16384
	ds_read_b128 v[40:43], v19 offset:20480
	ds_read_b128 v[44:47], v19 offset:24576
	ds_read_b128 v[48:51], v19 offset:28672
	s_waitcnt lgkmcnt(7)
	v_mov_b32_e32 v60, v20
	s_waitcnt lgkmcnt(6)
	v_mov_b32_e32 v61, v24
	s_waitcnt lgkmcnt(5)
	v_mov_b32_e32 v62, v28
	s_waitcnt lgkmcnt(4)
	v_mov_b32_e32 v63, v32
	s_waitcnt lgkmcnt(3)
	v_mov_b32_e32 v64, v36
	s_waitcnt lgkmcnt(2)
	v_mov_b32_e32 v65, v40
	s_waitcnt lgkmcnt(1)
	v_mov_b32_e32 v66, v44
	s_waitcnt lgkmcnt(0)
	v_mov_b32_e32 v67, v48
	v_mov_b32_e32 v24, v21
	v_mov_b32_e32 v32, v29
	v_mov_b32_e32 v40, v37
	v_mov_b32_e32 v48, v45
	v_mov_b32_e32 v20, v22
	v_mov_b32_e32 v21, v26
	v_mov_b32_e32 v28, v30
	v_mov_b32_e32 v29, v34
	v_mov_b32_e32 v36, v38
	v_mov_b32_e32 v37, v42
	v_mov_b32_e32 v44, v46
	v_mov_b32_e32 v45, v50
	v_mov_b32_e32 v26, v23
	v_mov_b32_e32 v34, v31
	v_mov_b32_e32 v42, v39
	v_mov_b32_e32 v50, v47
	v_add_u32_e32 v19, 16, v19
	v_pk_fma_f32 v[10:11], v[76:77], v[60:61], v[10:11] op_sel_hi:[0,1,1]
	v_pk_fma_f32 v[12:13], v[76:77], v[62:63], v[12:13] op_sel_hi:[0,1,1]
	v_pk_fma_f32 v[14:15], v[76:77], v[64:65], v[14:15] op_sel_hi:[0,1,1]
	v_pk_fma_f32 v[8:9], v[76:77], v[66:67], v[8:9] op_sel_hi:[0,1,1]
	v_pk_fma_f32 v[10:11], v[78:79], v[24:25], v[10:11] op_sel_hi:[0,1,1]
	v_pk_fma_f32 v[12:13], v[78:79], v[32:33], v[12:13] op_sel_hi:[0,1,1]
	v_pk_fma_f32 v[14:15], v[78:79], v[40:41], v[14:15] op_sel_hi:[0,1,1]
	v_pk_fma_f32 v[8:9], v[78:79], v[48:49], v[8:9] op_sel_hi:[0,1,1]
	v_pk_fma_f32 v[10:11], v[80:81], v[20:21], v[10:11] op_sel_hi:[0,1,1]
	v_pk_fma_f32 v[12:13], v[80:81], v[28:29], v[12:13] op_sel_hi:[0,1,1]
	v_pk_fma_f32 v[14:15], v[80:81], v[36:37], v[14:15] op_sel_hi:[0,1,1]
	v_pk_fma_f32 v[8:9], v[80:81], v[44:45], v[8:9] op_sel_hi:[0,1,1]
	v_pk_fma_f32 v[10:11], v[82:83], v[26:27], v[10:11] op_sel_hi:[0,1,1]
	v_pk_fma_f32 v[12:13], v[82:83], v[34:35], v[12:13] op_sel_hi:[0,1,1]
	v_pk_fma_f32 v[14:15], v[82:83], v[42:43], v[14:15] op_sel_hi:[0,1,1]
	v_pk_fma_f32 v[8:9], v[82:83], v[50:51], v[8:9] op_sel_hi:[0,1,1]
	v_lshl_add_u64 v[20:21], v[6:7], 0, s[6:7]
	v_add_co_u32_e32 v22, vcc, s84, v20
	global_load_dword v76, v[20:21], off nt
	s_nop 0
	v_addc_co_u32_e32 v23, vcc, 0, v21, vcc
	v_add_co_u32_e32 v24, vcc, s33, v20
	s_mov_b32 s13, 0x12000
	s_nop 0
	v_addc_co_u32_e32 v25, vcc, 0, v21, vcc
	v_add_co_u32_e32 v20, vcc, s13, v20
	s_add_u32 s6, s6, 0x18000
	s_addc_u32 s7, s7, 0
	v_addc_co_u32_e32 v21, vcc, 0, v21, vcc
	global_load_dword v78, v[22:23], off nt
	global_load_dword v80, v[24:25], off nt
	global_load_dword v82, v[20:21], off nt
	s_waitcnt vmcnt(28)
	ds_read_b128 v[20:23], v19
	ds_read_b128 v[24:27], v19 offset:4096
	ds_read_b128 v[28:31], v19 offset:8192
	ds_read_b128 v[32:35], v19 offset:12288
	ds_read_b128 v[36:39], v19 offset:16384
	ds_read_b128 v[40:43], v19 offset:20480
	ds_read_b128 v[44:47], v19 offset:24576
	ds_read_b128 v[48:51], v19 offset:28672
	s_waitcnt lgkmcnt(7)
	v_mov_b32_e32 v60, v20
	s_waitcnt lgkmcnt(6)
	v_mov_b32_e32 v61, v24
	s_waitcnt lgkmcnt(5)
	v_mov_b32_e32 v62, v28
	s_waitcnt lgkmcnt(4)
	v_mov_b32_e32 v63, v32
	s_waitcnt lgkmcnt(3)
	v_mov_b32_e32 v64, v36
	s_waitcnt lgkmcnt(2)
	v_mov_b32_e32 v65, v40
	s_waitcnt lgkmcnt(1)
	v_mov_b32_e32 v66, v44
	s_waitcnt lgkmcnt(0)
	v_mov_b32_e32 v67, v48
	v_mov_b32_e32 v24, v21
	v_mov_b32_e32 v32, v29
	v_mov_b32_e32 v40, v37
	v_mov_b32_e32 v48, v45
	v_mov_b32_e32 v20, v22
	v_mov_b32_e32 v21, v26
	v_mov_b32_e32 v28, v30
	v_mov_b32_e32 v29, v34
	v_mov_b32_e32 v36, v38
	v_mov_b32_e32 v37, v42
	v_mov_b32_e32 v44, v46
	v_mov_b32_e32 v45, v50
	v_mov_b32_e32 v26, v23
	v_mov_b32_e32 v34, v31
	v_mov_b32_e32 v42, v39
	v_mov_b32_e32 v50, v47
	v_add_u32_e32 v19, 16, v19
	v_pk_fma_f32 v[10:11], v[84:85], v[60:61], v[10:11] op_sel_hi:[0,1,1]
	v_pk_fma_f32 v[12:13], v[84:85], v[62:63], v[12:13] op_sel_hi:[0,1,1]
	v_pk_fma_f32 v[14:15], v[84:85], v[64:65], v[14:15] op_sel_hi:[0,1,1]
	v_pk_fma_f32 v[8:9], v[84:85], v[66:67], v[8:9] op_sel_hi:[0,1,1]
	v_pk_fma_f32 v[10:11], v[86:87], v[24:25], v[10:11] op_sel_hi:[0,1,1]
	v_pk_fma_f32 v[12:13], v[86:87], v[32:33], v[12:13] op_sel_hi:[0,1,1]
	v_pk_fma_f32 v[14:15], v[86:87], v[40:41], v[14:15] op_sel_hi:[0,1,1]
	v_pk_fma_f32 v[8:9], v[86:87], v[48:49], v[8:9] op_sel_hi:[0,1,1]
	v_pk_fma_f32 v[10:11], v[88:89], v[20:21], v[10:11] op_sel_hi:[0,1,1]
	v_pk_fma_f32 v[12:13], v[88:89], v[28:29], v[12:13] op_sel_hi:[0,1,1]
	v_pk_fma_f32 v[14:15], v[88:89], v[36:37], v[14:15] op_sel_hi:[0,1,1]
	v_pk_fma_f32 v[8:9], v[88:89], v[44:45], v[8:9] op_sel_hi:[0,1,1]
	v_pk_fma_f32 v[10:11], v[90:91], v[26:27], v[10:11] op_sel_hi:[0,1,1]
	v_pk_fma_f32 v[12:13], v[90:91], v[34:35], v[12:13] op_sel_hi:[0,1,1]
	v_pk_fma_f32 v[14:15], v[90:91], v[42:43], v[14:15] op_sel_hi:[0,1,1]
	v_pk_fma_f32 v[8:9], v[90:91], v[50:51], v[8:9] op_sel_hi:[0,1,1]
	v_lshl_add_u64 v[20:21], v[6:7], 0, s[6:7]
	v_add_co_u32_e32 v22, vcc, s84, v20
	global_load_dword v84, v[20:21], off nt
	s_nop 0
	v_addc_co_u32_e32 v23, vcc, 0, v21, vcc
	v_add_co_u32_e32 v24, vcc, s33, v20
	s_mov_b32 s13, 0x12000
	s_nop 0
	v_addc_co_u32_e32 v25, vcc, 0, v21, vcc
	v_add_co_u32_e32 v20, vcc, s13, v20
	s_add_u32 s6, s6, 0x18000
	s_addc_u32 s7, s7, 0
	v_addc_co_u32_e32 v21, vcc, 0, v21, vcc
	global_load_dword v86, v[22:23], off nt
	global_load_dword v88, v[24:25], off nt
	global_load_dword v90, v[20:21], off nt
	s_waitcnt vmcnt(28)
	ds_read_b128 v[20:23], v19
	ds_read_b128 v[24:27], v19 offset:4096
	ds_read_b128 v[28:31], v19 offset:8192
	ds_read_b128 v[32:35], v19 offset:12288
	ds_read_b128 v[36:39], v19 offset:16384
	ds_read_b128 v[40:43], v19 offset:20480
	ds_read_b128 v[44:47], v19 offset:24576
	ds_read_b128 v[48:51], v19 offset:28672
	s_waitcnt lgkmcnt(7)
	v_mov_b32_e32 v60, v20
	s_waitcnt lgkmcnt(6)
	v_mov_b32_e32 v61, v24
	s_waitcnt lgkmcnt(5)
	v_mov_b32_e32 v62, v28
	s_waitcnt lgkmcnt(4)
	v_mov_b32_e32 v63, v32
	s_waitcnt lgkmcnt(3)
	v_mov_b32_e32 v64, v36
	s_waitcnt lgkmcnt(2)
	v_mov_b32_e32 v65, v40
	s_waitcnt lgkmcnt(1)
	v_mov_b32_e32 v66, v44
	s_waitcnt lgkmcnt(0)
	v_mov_b32_e32 v67, v48
	v_mov_b32_e32 v24, v21
	v_mov_b32_e32 v32, v29
	v_mov_b32_e32 v40, v37
	v_mov_b32_e32 v48, v45
	v_mov_b32_e32 v20, v22
	v_mov_b32_e32 v21, v26
	v_mov_b32_e32 v28, v30
	v_mov_b32_e32 v29, v34
	v_mov_b32_e32 v36, v38
	v_mov_b32_e32 v37, v42
	v_mov_b32_e32 v44, v46
	v_mov_b32_e32 v45, v50
	v_mov_b32_e32 v26, v23
	v_mov_b32_e32 v34, v31
	v_mov_b32_e32 v42, v39
	v_mov_b32_e32 v50, v47
	v_add_u32_e32 v19, 16, v19
	v_pk_fma_f32 v[10:11], v[92:93], v[60:61], v[10:11] op_sel_hi:[0,1,1]
	v_pk_fma_f32 v[12:13], v[92:93], v[62:63], v[12:13] op_sel_hi:[0,1,1]
	v_pk_fma_f32 v[14:15], v[92:93], v[64:65], v[14:15] op_sel_hi:[0,1,1]
	v_pk_fma_f32 v[8:9], v[92:93], v[66:67], v[8:9] op_sel_hi:[0,1,1]
	v_pk_fma_f32 v[10:11], v[94:95], v[24:25], v[10:11] op_sel_hi:[0,1,1]
	v_pk_fma_f32 v[12:13], v[94:95], v[32:33], v[12:13] op_sel_hi:[0,1,1]
	v_pk_fma_f32 v[14:15], v[94:95], v[40:41], v[14:15] op_sel_hi:[0,1,1]
	v_pk_fma_f32 v[8:9], v[94:95], v[48:49], v[8:9] op_sel_hi:[0,1,1]
	v_pk_fma_f32 v[10:11], v[96:97], v[20:21], v[10:11] op_sel_hi:[0,1,1]
	v_pk_fma_f32 v[12:13], v[96:97], v[28:29], v[12:13] op_sel_hi:[0,1,1]
	v_pk_fma_f32 v[14:15], v[96:97], v[36:37], v[14:15] op_sel_hi:[0,1,1]
	v_pk_fma_f32 v[8:9], v[96:97], v[44:45], v[8:9] op_sel_hi:[0,1,1]
	v_pk_fma_f32 v[10:11], v[98:99], v[26:27], v[10:11] op_sel_hi:[0,1,1]
	v_pk_fma_f32 v[12:13], v[98:99], v[34:35], v[12:13] op_sel_hi:[0,1,1]
	v_pk_fma_f32 v[14:15], v[98:99], v[42:43], v[14:15] op_sel_hi:[0,1,1]
	v_pk_fma_f32 v[8:9], v[98:99], v[50:51], v[8:9] op_sel_hi:[0,1,1]
	v_lshl_add_u64 v[20:21], v[6:7], 0, s[6:7]
	v_add_co_u32_e32 v22, vcc, s84, v20
	global_load_dword v92, v[20:21], off nt
	s_nop 0
	v_addc_co_u32_e32 v23, vcc, 0, v21, vcc
	v_add_co_u32_e32 v24, vcc, s33, v20
	s_mov_b32 s13, 0x12000
	s_nop 0
	v_addc_co_u32_e32 v25, vcc, 0, v21, vcc
	v_add_co_u32_e32 v20, vcc, s13, v20
	s_add_u32 s6, s6, 0x18000
	s_addc_u32 s7, s7, 0
	v_addc_co_u32_e32 v21, vcc, 0, v21, vcc
	global_load_dword v94, v[22:23], off nt
	global_load_dword v96, v[24:25], off nt
	global_load_dword v98, v[20:21], off nt
	s_waitcnt vmcnt(28)
	ds_read_b128 v[20:23], v19
	ds_read_b128 v[24:27], v19 offset:4096
	ds_read_b128 v[28:31], v19 offset:8192
	ds_read_b128 v[32:35], v19 offset:12288
	ds_read_b128 v[36:39], v19 offset:16384
	ds_read_b128 v[40:43], v19 offset:20480
	ds_read_b128 v[44:47], v19 offset:24576
	ds_read_b128 v[48:51], v19 offset:28672
	s_waitcnt lgkmcnt(7)
	v_mov_b32_e32 v60, v20
	s_waitcnt lgkmcnt(6)
	v_mov_b32_e32 v61, v24
	s_waitcnt lgkmcnt(5)
	v_mov_b32_e32 v62, v28
	s_waitcnt lgkmcnt(4)
	v_mov_b32_e32 v63, v32
	s_waitcnt lgkmcnt(3)
	v_mov_b32_e32 v64, v36
	s_waitcnt lgkmcnt(2)
	v_mov_b32_e32 v65, v40
	s_waitcnt lgkmcnt(1)
	v_mov_b32_e32 v66, v44
	s_waitcnt lgkmcnt(0)
	v_mov_b32_e32 v67, v48
	v_mov_b32_e32 v24, v21
	v_mov_b32_e32 v32, v29
	v_mov_b32_e32 v40, v37
	v_mov_b32_e32 v48, v45
	v_mov_b32_e32 v20, v22
	v_mov_b32_e32 v21, v26
	v_mov_b32_e32 v28, v30
	v_mov_b32_e32 v29, v34
	v_mov_b32_e32 v36, v38
	v_mov_b32_e32 v37, v42
	v_mov_b32_e32 v44, v46
	v_mov_b32_e32 v45, v50
	v_mov_b32_e32 v26, v23
	v_mov_b32_e32 v34, v31
	v_mov_b32_e32 v42, v39
	v_mov_b32_e32 v50, v47
	v_add_u32_e32 v19, 16, v19
	v_pk_fma_f32 v[10:11], v[100:101], v[60:61], v[10:11] op_sel_hi:[0,1,1]
	v_pk_fma_f32 v[12:13], v[100:101], v[62:63], v[12:13] op_sel_hi:[0,1,1]
	v_pk_fma_f32 v[14:15], v[100:101], v[64:65], v[14:15] op_sel_hi:[0,1,1]
	v_pk_fma_f32 v[8:9], v[100:101], v[66:67], v[8:9] op_sel_hi:[0,1,1]
	v_pk_fma_f32 v[10:11], v[102:103], v[24:25], v[10:11] op_sel_hi:[0,1,1]
	v_pk_fma_f32 v[12:13], v[102:103], v[32:33], v[12:13] op_sel_hi:[0,1,1]
	v_pk_fma_f32 v[14:15], v[102:103], v[40:41], v[14:15] op_sel_hi:[0,1,1]
	v_pk_fma_f32 v[8:9], v[102:103], v[48:49], v[8:9] op_sel_hi:[0,1,1]
	v_pk_fma_f32 v[10:11], v[104:105], v[20:21], v[10:11] op_sel_hi:[0,1,1]
	v_pk_fma_f32 v[12:13], v[104:105], v[28:29], v[12:13] op_sel_hi:[0,1,1]
	v_pk_fma_f32 v[14:15], v[104:105], v[36:37], v[14:15] op_sel_hi:[0,1,1]
	v_pk_fma_f32 v[8:9], v[104:105], v[44:45], v[8:9] op_sel_hi:[0,1,1]
	v_pk_fma_f32 v[10:11], v[106:107], v[26:27], v[10:11] op_sel_hi:[0,1,1]
	v_pk_fma_f32 v[12:13], v[106:107], v[34:35], v[12:13] op_sel_hi:[0,1,1]
	v_pk_fma_f32 v[14:15], v[106:107], v[42:43], v[14:15] op_sel_hi:[0,1,1]
	v_pk_fma_f32 v[8:9], v[106:107], v[50:51], v[8:9] op_sel_hi:[0,1,1]
	v_lshl_add_u64 v[20:21], v[6:7], 0, s[6:7]
	v_add_co_u32_e32 v22, vcc, s84, v20
	global_load_dword v100, v[20:21], off nt
	s_nop 0
	v_addc_co_u32_e32 v23, vcc, 0, v21, vcc
	v_add_co_u32_e32 v24, vcc, s33, v20
	s_mov_b32 s13, 0x12000
	s_nop 0
	v_addc_co_u32_e32 v25, vcc, 0, v21, vcc
	v_add_co_u32_e32 v20, vcc, s13, v20
	s_add_u32 s6, s6, 0x18000
	s_addc_u32 s7, s7, 0
	v_addc_co_u32_e32 v21, vcc, 0, v21, vcc
	global_load_dword v102, v[22:23], off nt
	global_load_dword v104, v[24:25], off nt
	global_load_dword v106, v[20:21], off nt
	s_waitcnt vmcnt(28)
	ds_read_b128 v[20:23], v19
	ds_read_b128 v[24:27], v19 offset:4096
	ds_read_b128 v[28:31], v19 offset:8192
	ds_read_b128 v[32:35], v19 offset:12288
	ds_read_b128 v[36:39], v19 offset:16384
	ds_read_b128 v[40:43], v19 offset:20480
	ds_read_b128 v[44:47], v19 offset:24576
	ds_read_b128 v[48:51], v19 offset:28672
	s_waitcnt lgkmcnt(7)
	v_mov_b32_e32 v60, v20
	s_waitcnt lgkmcnt(6)
	v_mov_b32_e32 v61, v24
	s_waitcnt lgkmcnt(5)
	v_mov_b32_e32 v62, v28
	s_waitcnt lgkmcnt(4)
	v_mov_b32_e32 v63, v32
	s_waitcnt lgkmcnt(3)
	v_mov_b32_e32 v64, v36
	s_waitcnt lgkmcnt(2)
	v_mov_b32_e32 v65, v40
	s_waitcnt lgkmcnt(1)
	v_mov_b32_e32 v66, v44
	s_waitcnt lgkmcnt(0)
	v_mov_b32_e32 v67, v48
	v_mov_b32_e32 v24, v21
	v_mov_b32_e32 v32, v29
	v_mov_b32_e32 v40, v37
	v_mov_b32_e32 v48, v45
	v_mov_b32_e32 v20, v22
	v_mov_b32_e32 v21, v26
	v_mov_b32_e32 v28, v30
	v_mov_b32_e32 v29, v34
	v_mov_b32_e32 v36, v38
	v_mov_b32_e32 v37, v42
	v_mov_b32_e32 v44, v46
	v_mov_b32_e32 v45, v50
	v_mov_b32_e32 v26, v23
	v_mov_b32_e32 v34, v31
	v_mov_b32_e32 v42, v39
	v_mov_b32_e32 v50, v47
	v_add_u32_e32 v19, 16, v19
	v_pk_fma_f32 v[10:11], v[108:109], v[60:61], v[10:11] op_sel_hi:[0,1,1]
	v_pk_fma_f32 v[12:13], v[108:109], v[62:63], v[12:13] op_sel_hi:[0,1,1]
	v_pk_fma_f32 v[14:15], v[108:109], v[64:65], v[14:15] op_sel_hi:[0,1,1]
	v_pk_fma_f32 v[8:9], v[108:109], v[66:67], v[8:9] op_sel_hi:[0,1,1]
	v_pk_fma_f32 v[10:11], v[110:111], v[24:25], v[10:11] op_sel_hi:[0,1,1]
	v_pk_fma_f32 v[12:13], v[110:111], v[32:33], v[12:13] op_sel_hi:[0,1,1]
	v_pk_fma_f32 v[14:15], v[110:111], v[40:41], v[14:15] op_sel_hi:[0,1,1]
	v_pk_fma_f32 v[8:9], v[110:111], v[48:49], v[8:9] op_sel_hi:[0,1,1]
	v_pk_fma_f32 v[10:11], v[112:113], v[20:21], v[10:11] op_sel_hi:[0,1,1]
	v_pk_fma_f32 v[12:13], v[112:113], v[28:29], v[12:13] op_sel_hi:[0,1,1]
	v_pk_fma_f32 v[14:15], v[112:113], v[36:37], v[14:15] op_sel_hi:[0,1,1]
	v_pk_fma_f32 v[8:9], v[112:113], v[44:45], v[8:9] op_sel_hi:[0,1,1]
	v_pk_fma_f32 v[10:11], v[114:115], v[26:27], v[10:11] op_sel_hi:[0,1,1]
	v_pk_fma_f32 v[12:13], v[114:115], v[34:35], v[12:13] op_sel_hi:[0,1,1]
	v_pk_fma_f32 v[14:15], v[114:115], v[42:43], v[14:15] op_sel_hi:[0,1,1]
	v_pk_fma_f32 v[8:9], v[114:115], v[50:51], v[8:9] op_sel_hi:[0,1,1]
	v_lshl_add_u64 v[20:21], v[6:7], 0, s[6:7]
	v_add_co_u32_e32 v22, vcc, s84, v20
	global_load_dword v108, v[20:21], off nt
	s_nop 0
	v_addc_co_u32_e32 v23, vcc, 0, v21, vcc
	v_add_co_u32_e32 v24, vcc, s33, v20
	s_mov_b32 s13, 0x12000
	s_nop 0
	v_addc_co_u32_e32 v25, vcc, 0, v21, vcc
	v_add_co_u32_e32 v20, vcc, s13, v20
	s_add_u32 s6, s6, 0x18000
	s_addc_u32 s7, s7, 0
	v_addc_co_u32_e32 v21, vcc, 0, v21, vcc
	global_load_dword v110, v[22:23], off nt
	global_load_dword v112, v[24:25], off nt
	global_load_dword v114, v[20:21], off nt
	s_waitcnt vmcnt(28)
	ds_read_b128 v[20:23], v19
	ds_read_b128 v[24:27], v19 offset:4096
	ds_read_b128 v[28:31], v19 offset:8192
	ds_read_b128 v[32:35], v19 offset:12288
	ds_read_b128 v[36:39], v19 offset:16384
	ds_read_b128 v[40:43], v19 offset:20480
	ds_read_b128 v[44:47], v19 offset:24576
	ds_read_b128 v[48:51], v19 offset:28672
	s_waitcnt lgkmcnt(7)
	v_mov_b32_e32 v60, v20
	s_waitcnt lgkmcnt(6)
	v_mov_b32_e32 v61, v24
	s_waitcnt lgkmcnt(5)
	v_mov_b32_e32 v62, v28
	s_waitcnt lgkmcnt(4)
	v_mov_b32_e32 v63, v32
	s_waitcnt lgkmcnt(3)
	v_mov_b32_e32 v64, v36
	s_waitcnt lgkmcnt(2)
	v_mov_b32_e32 v65, v40
	s_waitcnt lgkmcnt(1)
	v_mov_b32_e32 v66, v44
	s_waitcnt lgkmcnt(0)
	v_mov_b32_e32 v67, v48
	v_mov_b32_e32 v24, v21
	v_mov_b32_e32 v32, v29
	v_mov_b32_e32 v40, v37
	v_mov_b32_e32 v48, v45
	v_mov_b32_e32 v20, v22
	v_mov_b32_e32 v21, v26
	v_mov_b32_e32 v28, v30
	v_mov_b32_e32 v29, v34
	v_mov_b32_e32 v36, v38
	v_mov_b32_e32 v37, v42
	v_mov_b32_e32 v44, v46
	v_mov_b32_e32 v45, v50
	v_mov_b32_e32 v26, v23
	v_mov_b32_e32 v34, v31
	v_mov_b32_e32 v42, v39
	v_mov_b32_e32 v50, v47
	v_add_u32_e32 v19, 16, v19
	v_pk_fma_f32 v[10:11], v[116:117], v[60:61], v[10:11] op_sel_hi:[0,1,1]
	v_pk_fma_f32 v[12:13], v[116:117], v[62:63], v[12:13] op_sel_hi:[0,1,1]
	v_pk_fma_f32 v[14:15], v[116:117], v[64:65], v[14:15] op_sel_hi:[0,1,1]
	v_pk_fma_f32 v[8:9], v[116:117], v[66:67], v[8:9] op_sel_hi:[0,1,1]
	v_pk_fma_f32 v[10:11], v[118:119], v[24:25], v[10:11] op_sel_hi:[0,1,1]
	v_pk_fma_f32 v[12:13], v[118:119], v[32:33], v[12:13] op_sel_hi:[0,1,1]
	v_pk_fma_f32 v[14:15], v[118:119], v[40:41], v[14:15] op_sel_hi:[0,1,1]
	v_pk_fma_f32 v[8:9], v[118:119], v[48:49], v[8:9] op_sel_hi:[0,1,1]
	v_pk_fma_f32 v[10:11], v[120:121], v[20:21], v[10:11] op_sel_hi:[0,1,1]
	v_pk_fma_f32 v[12:13], v[120:121], v[28:29], v[12:13] op_sel_hi:[0,1,1]
	v_pk_fma_f32 v[14:15], v[120:121], v[36:37], v[14:15] op_sel_hi:[0,1,1]
	v_pk_fma_f32 v[8:9], v[120:121], v[44:45], v[8:9] op_sel_hi:[0,1,1]
	v_pk_fma_f32 v[10:11], v[122:123], v[26:27], v[10:11] op_sel_hi:[0,1,1]
	v_pk_fma_f32 v[12:13], v[122:123], v[34:35], v[12:13] op_sel_hi:[0,1,1]
	v_pk_fma_f32 v[14:15], v[122:123], v[42:43], v[14:15] op_sel_hi:[0,1,1]
	v_pk_fma_f32 v[8:9], v[122:123], v[50:51], v[8:9] op_sel_hi:[0,1,1]
	v_lshl_add_u64 v[20:21], v[6:7], 0, s[6:7]
	v_add_co_u32_e32 v22, vcc, s84, v20
	global_load_dword v116, v[20:21], off nt
	s_nop 0
	v_addc_co_u32_e32 v23, vcc, 0, v21, vcc
	v_add_co_u32_e32 v24, vcc, s33, v20
	s_mov_b32 s13, 0x12000
	s_nop 0
	v_addc_co_u32_e32 v25, vcc, 0, v21, vcc
	v_add_co_u32_e32 v20, vcc, s13, v20
	s_add_u32 s6, s6, 0x18000
	s_addc_u32 s7, s7, 0
	v_addc_co_u32_e32 v21, vcc, 0, v21, vcc
	global_load_dword v118, v[22:23], off nt
	global_load_dword v120, v[24:25], off nt
	global_load_dword v122, v[20:21], off nt
	s_waitcnt vmcnt(28)
	ds_read_b128 v[20:23], v19
	ds_read_b128 v[24:27], v19 offset:4096
	ds_read_b128 v[28:31], v19 offset:8192
	ds_read_b128 v[32:35], v19 offset:12288
	ds_read_b128 v[36:39], v19 offset:16384
	ds_read_b128 v[40:43], v19 offset:20480
	ds_read_b128 v[44:47], v19 offset:24576
	ds_read_b128 v[48:51], v19 offset:28672
	s_waitcnt lgkmcnt(7)
	v_mov_b32_e32 v60, v20
	s_waitcnt lgkmcnt(6)
	v_mov_b32_e32 v61, v24
	s_waitcnt lgkmcnt(5)
	v_mov_b32_e32 v62, v28
	s_waitcnt lgkmcnt(4)
	v_mov_b32_e32 v63, v32
	s_waitcnt lgkmcnt(3)
	v_mov_b32_e32 v64, v36
	s_waitcnt lgkmcnt(2)
	v_mov_b32_e32 v65, v40
	s_waitcnt lgkmcnt(1)
	v_mov_b32_e32 v66, v44
	s_waitcnt lgkmcnt(0)
	v_mov_b32_e32 v67, v48
	v_mov_b32_e32 v24, v21
	v_mov_b32_e32 v32, v29
	v_mov_b32_e32 v40, v37
	v_mov_b32_e32 v48, v45
	v_mov_b32_e32 v20, v22
	v_mov_b32_e32 v21, v26
	v_mov_b32_e32 v28, v30
	v_mov_b32_e32 v29, v34
	v_mov_b32_e32 v36, v38
	v_mov_b32_e32 v37, v42
	v_mov_b32_e32 v44, v46
	v_mov_b32_e32 v45, v50
	v_mov_b32_e32 v26, v23
	v_mov_b32_e32 v34, v31
	v_mov_b32_e32 v42, v39
	v_mov_b32_e32 v50, v47
	v_add_u32_e32 v19, 16, v19
	v_pk_fma_f32 v[10:11], v[140:141], v[60:61], v[10:11] op_sel_hi:[0,1,1]
	v_pk_fma_f32 v[12:13], v[140:141], v[62:63], v[12:13] op_sel_hi:[0,1,1]
	v_pk_fma_f32 v[14:15], v[140:141], v[64:65], v[14:15] op_sel_hi:[0,1,1]
	v_pk_fma_f32 v[8:9], v[140:141], v[66:67], v[8:9] op_sel_hi:[0,1,1]
	v_pk_fma_f32 v[10:11], v[142:143], v[24:25], v[10:11] op_sel_hi:[0,1,1]
	v_pk_fma_f32 v[12:13], v[142:143], v[32:33], v[12:13] op_sel_hi:[0,1,1]
	v_pk_fma_f32 v[14:15], v[142:143], v[40:41], v[14:15] op_sel_hi:[0,1,1]
	v_pk_fma_f32 v[8:9], v[142:143], v[48:49], v[8:9] op_sel_hi:[0,1,1]
	v_pk_fma_f32 v[10:11], v[144:145], v[20:21], v[10:11] op_sel_hi:[0,1,1]
	v_pk_fma_f32 v[12:13], v[144:145], v[28:29], v[12:13] op_sel_hi:[0,1,1]
	v_pk_fma_f32 v[14:15], v[144:145], v[36:37], v[14:15] op_sel_hi:[0,1,1]
	v_pk_fma_f32 v[8:9], v[144:145], v[44:45], v[8:9] op_sel_hi:[0,1,1]
	v_pk_fma_f32 v[10:11], v[146:147], v[26:27], v[10:11] op_sel_hi:[0,1,1]
	v_pk_fma_f32 v[12:13], v[146:147], v[34:35], v[12:13] op_sel_hi:[0,1,1]
	v_pk_fma_f32 v[14:15], v[146:147], v[42:43], v[14:15] op_sel_hi:[0,1,1]
	v_pk_fma_f32 v[8:9], v[146:147], v[50:51], v[8:9] op_sel_hi:[0,1,1]
	v_lshl_add_u64 v[20:21], v[6:7], 0, s[6:7]
	v_add_co_u32_e32 v22, vcc, s84, v20
	global_load_dword v140, v[20:21], off nt
	s_nop 0
	v_addc_co_u32_e32 v23, vcc, 0, v21, vcc
	v_add_co_u32_e32 v24, vcc, s33, v20
	s_mov_b32 s13, 0x12000
	s_nop 0
	v_addc_co_u32_e32 v25, vcc, 0, v21, vcc
	v_add_co_u32_e32 v20, vcc, s13, v20
	s_add_u32 s6, s6, 0x18000
	s_addc_u32 s7, s7, 0
	v_addc_co_u32_e32 v21, vcc, 0, v21, vcc
	global_load_dword v142, v[22:23], off nt
	global_load_dword v144, v[24:25], off nt
	global_load_dword v146, v[20:21], off nt
	s_add_i32 s100, s100, 1
	s_cmp_lt_u32 s100, 3
	s_cbranch_scc1 .Lph0_loop
	s_waitcnt vmcnt(28)
	ds_read_b128 v[20:23], v19
	ds_read_b128 v[24:27], v19 offset:4096
	ds_read_b128 v[28:31], v19 offset:8192
	ds_read_b128 v[32:35], v19 offset:12288
	ds_read_b128 v[36:39], v19 offset:16384
	ds_read_b128 v[40:43], v19 offset:20480
	ds_read_b128 v[44:47], v19 offset:24576
	ds_read_b128 v[48:51], v19 offset:28672
	s_waitcnt lgkmcnt(7)
	v_mov_b32_e32 v60, v20
	s_waitcnt lgkmcnt(6)
	v_mov_b32_e32 v61, v24
	s_waitcnt lgkmcnt(5)
	v_mov_b32_e32 v62, v28
	s_waitcnt lgkmcnt(4)
	v_mov_b32_e32 v63, v32
	s_waitcnt lgkmcnt(3)
	v_mov_b32_e32 v64, v36
	s_waitcnt lgkmcnt(2)
	v_mov_b32_e32 v65, v40
	s_waitcnt lgkmcnt(1)
	v_mov_b32_e32 v66, v44
	s_waitcnt lgkmcnt(0)
	v_mov_b32_e32 v67, v48
	v_mov_b32_e32 v24, v21
	v_mov_b32_e32 v32, v29
	v_mov_b32_e32 v40, v37
	v_mov_b32_e32 v48, v45
	v_mov_b32_e32 v20, v22
	v_mov_b32_e32 v21, v26
	v_mov_b32_e32 v28, v30
	v_mov_b32_e32 v29, v34
	v_mov_b32_e32 v36, v38
	v_mov_b32_e32 v37, v42
	v_mov_b32_e32 v44, v46
	v_mov_b32_e32 v45, v50
	v_mov_b32_e32 v26, v23
	v_mov_b32_e32 v34, v31
	v_mov_b32_e32 v42, v39
	v_mov_b32_e32 v50, v47
	v_add_u32_e32 v19, 16, v19
	v_pk_fma_f32 v[10:11], v[68:69], v[60:61], v[10:11] op_sel_hi:[0,1,1]
	v_pk_fma_f32 v[12:13], v[68:69], v[62:63], v[12:13] op_sel_hi:[0,1,1]
	v_pk_fma_f32 v[14:15], v[68:69], v[64:65], v[14:15] op_sel_hi:[0,1,1]
	v_pk_fma_f32 v[8:9], v[68:69], v[66:67], v[8:9] op_sel_hi:[0,1,1]
	v_pk_fma_f32 v[10:11], v[70:71], v[24:25], v[10:11] op_sel_hi:[0,1,1]
	v_pk_fma_f32 v[12:13], v[70:71], v[32:33], v[12:13] op_sel_hi:[0,1,1]
	v_pk_fma_f32 v[14:15], v[70:71], v[40:41], v[14:15] op_sel_hi:[0,1,1]
	v_pk_fma_f32 v[8:9], v[70:71], v[48:49], v[8:9] op_sel_hi:[0,1,1]
	v_pk_fma_f32 v[10:11], v[72:73], v[20:21], v[10:11] op_sel_hi:[0,1,1]
	v_pk_fma_f32 v[12:13], v[72:73], v[28:29], v[12:13] op_sel_hi:[0,1,1]
	v_pk_fma_f32 v[14:15], v[72:73], v[36:37], v[14:15] op_sel_hi:[0,1,1]
	v_pk_fma_f32 v[8:9], v[72:73], v[44:45], v[8:9] op_sel_hi:[0,1,1]
	v_pk_fma_f32 v[10:11], v[74:75], v[26:27], v[10:11] op_sel_hi:[0,1,1]
	v_pk_fma_f32 v[12:13], v[74:75], v[34:35], v[12:13] op_sel_hi:[0,1,1]
	v_pk_fma_f32 v[14:15], v[74:75], v[42:43], v[14:15] op_sel_hi:[0,1,1]
	v_pk_fma_f32 v[8:9], v[74:75], v[50:51], v[8:9] op_sel_hi:[0,1,1]
	s_waitcnt vmcnt(24)
	ds_read_b128 v[20:23], v19
	ds_read_b128 v[24:27], v19 offset:4096
	ds_read_b128 v[28:31], v19 offset:8192
	ds_read_b128 v[32:35], v19 offset:12288
	ds_read_b128 v[36:39], v19 offset:16384
	ds_read_b128 v[40:43], v19 offset:20480
	ds_read_b128 v[44:47], v19 offset:24576
	ds_read_b128 v[48:51], v19 offset:28672
	s_waitcnt lgkmcnt(7)
	v_mov_b32_e32 v60, v20
	s_waitcnt lgkmcnt(6)
	v_mov_b32_e32 v61, v24
	s_waitcnt lgkmcnt(5)
	v_mov_b32_e32 v62, v28
	s_waitcnt lgkmcnt(4)
	v_mov_b32_e32 v63, v32
	s_waitcnt lgkmcnt(3)
	v_mov_b32_e32 v64, v36
	s_waitcnt lgkmcnt(2)
	v_mov_b32_e32 v65, v40
	s_waitcnt lgkmcnt(1)
	v_mov_b32_e32 v66, v44
	s_waitcnt lgkmcnt(0)
	v_mov_b32_e32 v67, v48
	v_mov_b32_e32 v24, v21
	v_mov_b32_e32 v32, v29
	v_mov_b32_e32 v40, v37
	v_mov_b32_e32 v48, v45
	v_mov_b32_e32 v20, v22
	v_mov_b32_e32 v21, v26
	v_mov_b32_e32 v28, v30
	v_mov_b32_e32 v29, v34
	v_mov_b32_e32 v36, v38
	v_mov_b32_e32 v37, v42
	v_mov_b32_e32 v44, v46
	v_mov_b32_e32 v45, v50
	v_mov_b32_e32 v26, v23
	v_mov_b32_e32 v34, v31
	v_mov_b32_e32 v42, v39
	v_mov_b32_e32 v50, v47
	v_add_u32_e32 v19, 16, v19
	v_pk_fma_f32 v[10:11], v[76:77], v[60:61], v[10:11] op_sel_hi:[0,1,1]
	v_pk_fma_f32 v[12:13], v[76:77], v[62:63], v[12:13] op_sel_hi:[0,1,1]
	v_pk_fma_f32 v[14:15], v[76:77], v[64:65], v[14:15] op_sel_hi:[0,1,1]
	v_pk_fma_f32 v[8:9], v[76:77], v[66:67], v[8:9] op_sel_hi:[0,1,1]
	v_pk_fma_f32 v[10:11], v[78:79], v[24:25], v[10:11] op_sel_hi:[0,1,1]
	v_pk_fma_f32 v[12:13], v[78:79], v[32:33], v[12:13] op_sel_hi:[0,1,1]
	v_pk_fma_f32 v[14:15], v[78:79], v[40:41], v[14:15] op_sel_hi:[0,1,1]
	v_pk_fma_f32 v[8:9], v[78:79], v[48:49], v[8:9] op_sel_hi:[0,1,1]
	v_pk_fma_f32 v[10:11], v[80:81], v[20:21], v[10:11] op_sel_hi:[0,1,1]
	v_pk_fma_f32 v[12:13], v[80:81], v[28:29], v[12:13] op_sel_hi:[0,1,1]
	v_pk_fma_f32 v[14:15], v[80:81], v[36:37], v[14:15] op_sel_hi:[0,1,1]
	v_pk_fma_f32 v[8:9], v[80:81], v[44:45], v[8:9] op_sel_hi:[0,1,1]
	v_pk_fma_f32 v[10:11], v[82:83], v[26:27], v[10:11] op_sel_hi:[0,1,1]
	v_pk_fma_f32 v[12:13], v[82:83], v[34:35], v[12:13] op_sel_hi:[0,1,1]
	v_pk_fma_f32 v[14:15], v[82:83], v[42:43], v[14:15] op_sel_hi:[0,1,1]
	v_pk_fma_f32 v[8:9], v[82:83], v[50:51], v[8:9] op_sel_hi:[0,1,1]
	s_waitcnt vmcnt(20)
	ds_read_b128 v[20:23], v19
	ds_read_b128 v[24:27], v19 offset:4096
	ds_read_b128 v[28:31], v19 offset:8192
	ds_read_b128 v[32:35], v19 offset:12288
	ds_read_b128 v[36:39], v19 offset:16384
	ds_read_b128 v[40:43], v19 offset:20480
	ds_read_b128 v[44:47], v19 offset:24576
	ds_read_b128 v[48:51], v19 offset:28672
	s_waitcnt lgkmcnt(7)
	v_mov_b32_e32 v60, v20
	s_waitcnt lgkmcnt(6)
	v_mov_b32_e32 v61, v24
	s_waitcnt lgkmcnt(5)
	v_mov_b32_e32 v62, v28
	s_waitcnt lgkmcnt(4)
	v_mov_b32_e32 v63, v32
	s_waitcnt lgkmcnt(3)
	v_mov_b32_e32 v64, v36
	s_waitcnt lgkmcnt(2)
	v_mov_b32_e32 v65, v40
	s_waitcnt lgkmcnt(1)
	v_mov_b32_e32 v66, v44
	s_waitcnt lgkmcnt(0)
	v_mov_b32_e32 v67, v48
	v_mov_b32_e32 v24, v21
	v_mov_b32_e32 v32, v29
	v_mov_b32_e32 v40, v37
	v_mov_b32_e32 v48, v45
	v_mov_b32_e32 v20, v22
	v_mov_b32_e32 v21, v26
	v_mov_b32_e32 v28, v30
	v_mov_b32_e32 v29, v34
	v_mov_b32_e32 v36, v38
	v_mov_b32_e32 v37, v42
	v_mov_b32_e32 v44, v46
	v_mov_b32_e32 v45, v50
	v_mov_b32_e32 v26, v23
	v_mov_b32_e32 v34, v31
	v_mov_b32_e32 v42, v39
	v_mov_b32_e32 v50, v47
	v_add_u32_e32 v19, 16, v19
	v_pk_fma_f32 v[10:11], v[84:85], v[60:61], v[10:11] op_sel_hi:[0,1,1]
	v_pk_fma_f32 v[12:13], v[84:85], v[62:63], v[12:13] op_sel_hi:[0,1,1]
	v_pk_fma_f32 v[14:15], v[84:85], v[64:65], v[14:15] op_sel_hi:[0,1,1]
	v_pk_fma_f32 v[8:9], v[84:85], v[66:67], v[8:9] op_sel_hi:[0,1,1]
	v_pk_fma_f32 v[10:11], v[86:87], v[24:25], v[10:11] op_sel_hi:[0,1,1]
	v_pk_fma_f32 v[12:13], v[86:87], v[32:33], v[12:13] op_sel_hi:[0,1,1]
	v_pk_fma_f32 v[14:15], v[86:87], v[40:41], v[14:15] op_sel_hi:[0,1,1]
	v_pk_fma_f32 v[8:9], v[86:87], v[48:49], v[8:9] op_sel_hi:[0,1,1]
	v_pk_fma_f32 v[10:11], v[88:89], v[20:21], v[10:11] op_sel_hi:[0,1,1]
	v_pk_fma_f32 v[12:13], v[88:89], v[28:29], v[12:13] op_sel_hi:[0,1,1]
	v_pk_fma_f32 v[14:15], v[88:89], v[36:37], v[14:15] op_sel_hi:[0,1,1]
	v_pk_fma_f32 v[8:9], v[88:89], v[44:45], v[8:9] op_sel_hi:[0,1,1]
	v_pk_fma_f32 v[10:11], v[90:91], v[26:27], v[10:11] op_sel_hi:[0,1,1]
	v_pk_fma_f32 v[12:13], v[90:91], v[34:35], v[12:13] op_sel_hi:[0,1,1]
	v_pk_fma_f32 v[14:15], v[90:91], v[42:43], v[14:15] op_sel_hi:[0,1,1]
	v_pk_fma_f32 v[8:9], v[90:91], v[50:51], v[8:9] op_sel_hi:[0,1,1]
	s_waitcnt vmcnt(16)
	ds_read_b128 v[20:23], v19
	ds_read_b128 v[24:27], v19 offset:4096
	ds_read_b128 v[28:31], v19 offset:8192
	ds_read_b128 v[32:35], v19 offset:12288
	ds_read_b128 v[36:39], v19 offset:16384
	ds_read_b128 v[40:43], v19 offset:20480
	ds_read_b128 v[44:47], v19 offset:24576
	ds_read_b128 v[48:51], v19 offset:28672
	s_waitcnt lgkmcnt(7)
	v_mov_b32_e32 v60, v20
	s_waitcnt lgkmcnt(6)
	v_mov_b32_e32 v61, v24
	s_waitcnt lgkmcnt(5)
	v_mov_b32_e32 v62, v28
	s_waitcnt lgkmcnt(4)
	v_mov_b32_e32 v63, v32
	s_waitcnt lgkmcnt(3)
	v_mov_b32_e32 v64, v36
	s_waitcnt lgkmcnt(2)
	v_mov_b32_e32 v65, v40
	s_waitcnt lgkmcnt(1)
	v_mov_b32_e32 v66, v44
	s_waitcnt lgkmcnt(0)
	v_mov_b32_e32 v67, v48
	v_mov_b32_e32 v24, v21
	v_mov_b32_e32 v32, v29
	v_mov_b32_e32 v40, v37
	v_mov_b32_e32 v48, v45
	v_mov_b32_e32 v20, v22
	v_mov_b32_e32 v21, v26
	v_mov_b32_e32 v28, v30
	v_mov_b32_e32 v29, v34
	v_mov_b32_e32 v36, v38
	v_mov_b32_e32 v37, v42
	v_mov_b32_e32 v44, v46
	v_mov_b32_e32 v45, v50
	v_mov_b32_e32 v26, v23
	v_mov_b32_e32 v34, v31
	v_mov_b32_e32 v42, v39
	v_mov_b32_e32 v50, v47
	v_add_u32_e32 v19, 16, v19
	v_pk_fma_f32 v[10:11], v[92:93], v[60:61], v[10:11] op_sel_hi:[0,1,1]
	v_pk_fma_f32 v[12:13], v[92:93], v[62:63], v[12:13] op_sel_hi:[0,1,1]
	v_pk_fma_f32 v[14:15], v[92:93], v[64:65], v[14:15] op_sel_hi:[0,1,1]
	v_pk_fma_f32 v[8:9], v[92:93], v[66:67], v[8:9] op_sel_hi:[0,1,1]
	v_pk_fma_f32 v[10:11], v[94:95], v[24:25], v[10:11] op_sel_hi:[0,1,1]
	v_pk_fma_f32 v[12:13], v[94:95], v[32:33], v[12:13] op_sel_hi:[0,1,1]
	v_pk_fma_f32 v[14:15], v[94:95], v[40:41], v[14:15] op_sel_hi:[0,1,1]
	v_pk_fma_f32 v[8:9], v[94:95], v[48:49], v[8:9] op_sel_hi:[0,1,1]
	v_pk_fma_f32 v[10:11], v[96:97], v[20:21], v[10:11] op_sel_hi:[0,1,1]
	v_pk_fma_f32 v[12:13], v[96:97], v[28:29], v[12:13] op_sel_hi:[0,1,1]
	v_pk_fma_f32 v[14:15], v[96:97], v[36:37], v[14:15] op_sel_hi:[0,1,1]
	v_pk_fma_f32 v[8:9], v[96:97], v[44:45], v[8:9] op_sel_hi:[0,1,1]
	v_pk_fma_f32 v[10:11], v[98:99], v[26:27], v[10:11] op_sel_hi:[0,1,1]
	v_pk_fma_f32 v[12:13], v[98:99], v[34:35], v[12:13] op_sel_hi:[0,1,1]
	v_pk_fma_f32 v[14:15], v[98:99], v[42:43], v[14:15] op_sel_hi:[0,1,1]
	v_pk_fma_f32 v[8:9], v[98:99], v[50:51], v[8:9] op_sel_hi:[0,1,1]
	s_waitcnt vmcnt(12)
	ds_read_b128 v[20:23], v19
	ds_read_b128 v[24:27], v19 offset:4096
	ds_read_b128 v[28:31], v19 offset:8192
	ds_read_b128 v[32:35], v19 offset:12288
	ds_read_b128 v[36:39], v19 offset:16384
	ds_read_b128 v[40:43], v19 offset:20480
	ds_read_b128 v[44:47], v19 offset:24576
	ds_read_b128 v[48:51], v19 offset:28672
	s_waitcnt lgkmcnt(7)
	v_mov_b32_e32 v60, v20
	s_waitcnt lgkmcnt(6)
	v_mov_b32_e32 v61, v24
	s_waitcnt lgkmcnt(5)
	v_mov_b32_e32 v62, v28
	s_waitcnt lgkmcnt(4)
	v_mov_b32_e32 v63, v32
	s_waitcnt lgkmcnt(3)
	v_mov_b32_e32 v64, v36
	s_waitcnt lgkmcnt(2)
	v_mov_b32_e32 v65, v40
	s_waitcnt lgkmcnt(1)
	v_mov_b32_e32 v66, v44
	s_waitcnt lgkmcnt(0)
	v_mov_b32_e32 v67, v48
	v_mov_b32_e32 v24, v21
	v_mov_b32_e32 v32, v29
	v_mov_b32_e32 v40, v37
	v_mov_b32_e32 v48, v45
	v_mov_b32_e32 v20, v22
	v_mov_b32_e32 v21, v26
	v_mov_b32_e32 v28, v30
	v_mov_b32_e32 v29, v34
	v_mov_b32_e32 v36, v38
	v_mov_b32_e32 v37, v42
	v_mov_b32_e32 v44, v46
	v_mov_b32_e32 v45, v50
	v_mov_b32_e32 v26, v23
	v_mov_b32_e32 v34, v31
	v_mov_b32_e32 v42, v39
	v_mov_b32_e32 v50, v47
	v_add_u32_e32 v19, 16, v19
	v_pk_fma_f32 v[10:11], v[100:101], v[60:61], v[10:11] op_sel_hi:[0,1,1]
	v_pk_fma_f32 v[12:13], v[100:101], v[62:63], v[12:13] op_sel_hi:[0,1,1]
	v_pk_fma_f32 v[14:15], v[100:101], v[64:65], v[14:15] op_sel_hi:[0,1,1]
	v_pk_fma_f32 v[8:9], v[100:101], v[66:67], v[8:9] op_sel_hi:[0,1,1]
	v_pk_fma_f32 v[10:11], v[102:103], v[24:25], v[10:11] op_sel_hi:[0,1,1]
	v_pk_fma_f32 v[12:13], v[102:103], v[32:33], v[12:13] op_sel_hi:[0,1,1]
	v_pk_fma_f32 v[14:15], v[102:103], v[40:41], v[14:15] op_sel_hi:[0,1,1]
	v_pk_fma_f32 v[8:9], v[102:103], v[48:49], v[8:9] op_sel_hi:[0,1,1]
	v_pk_fma_f32 v[10:11], v[104:105], v[20:21], v[10:11] op_sel_hi:[0,1,1]
	v_pk_fma_f32 v[12:13], v[104:105], v[28:29], v[12:13] op_sel_hi:[0,1,1]
	v_pk_fma_f32 v[14:15], v[104:105], v[36:37], v[14:15] op_sel_hi:[0,1,1]
	v_pk_fma_f32 v[8:9], v[104:105], v[44:45], v[8:9] op_sel_hi:[0,1,1]
	v_pk_fma_f32 v[10:11], v[106:107], v[26:27], v[10:11] op_sel_hi:[0,1,1]
	v_pk_fma_f32 v[12:13], v[106:107], v[34:35], v[12:13] op_sel_hi:[0,1,1]
	v_pk_fma_f32 v[14:15], v[106:107], v[42:43], v[14:15] op_sel_hi:[0,1,1]
	v_pk_fma_f32 v[8:9], v[106:107], v[50:51], v[8:9] op_sel_hi:[0,1,1]
	s_waitcnt vmcnt(8)
	ds_read_b128 v[20:23], v19
	ds_read_b128 v[24:27], v19 offset:4096
	ds_read_b128 v[28:31], v19 offset:8192
	ds_read_b128 v[32:35], v19 offset:12288
	ds_read_b128 v[36:39], v19 offset:16384
	ds_read_b128 v[40:43], v19 offset:20480
	ds_read_b128 v[44:47], v19 offset:24576
	ds_read_b128 v[48:51], v19 offset:28672
	s_waitcnt lgkmcnt(7)
	v_mov_b32_e32 v60, v20
	s_waitcnt lgkmcnt(6)
	v_mov_b32_e32 v61, v24
	s_waitcnt lgkmcnt(5)
	v_mov_b32_e32 v62, v28
	s_waitcnt lgkmcnt(4)
	v_mov_b32_e32 v63, v32
	s_waitcnt lgkmcnt(3)
	v_mov_b32_e32 v64, v36
	s_waitcnt lgkmcnt(2)
	v_mov_b32_e32 v65, v40
	s_waitcnt lgkmcnt(1)
	v_mov_b32_e32 v66, v44
	s_waitcnt lgkmcnt(0)
	v_mov_b32_e32 v67, v48
	v_mov_b32_e32 v24, v21
	v_mov_b32_e32 v32, v29
	v_mov_b32_e32 v40, v37
	v_mov_b32_e32 v48, v45
	v_mov_b32_e32 v20, v22
	v_mov_b32_e32 v21, v26
	v_mov_b32_e32 v28, v30
	v_mov_b32_e32 v29, v34
	v_mov_b32_e32 v36, v38
	v_mov_b32_e32 v37, v42
	v_mov_b32_e32 v44, v46
	v_mov_b32_e32 v45, v50
	v_mov_b32_e32 v26, v23
	v_mov_b32_e32 v34, v31
	v_mov_b32_e32 v42, v39
	v_mov_b32_e32 v50, v47
	v_add_u32_e32 v19, 16, v19
	v_pk_fma_f32 v[10:11], v[108:109], v[60:61], v[10:11] op_sel_hi:[0,1,1]
	v_pk_fma_f32 v[12:13], v[108:109], v[62:63], v[12:13] op_sel_hi:[0,1,1]
	v_pk_fma_f32 v[14:15], v[108:109], v[64:65], v[14:15] op_sel_hi:[0,1,1]
	v_pk_fma_f32 v[8:9], v[108:109], v[66:67], v[8:9] op_sel_hi:[0,1,1]
	v_pk_fma_f32 v[10:11], v[110:111], v[24:25], v[10:11] op_sel_hi:[0,1,1]
	v_pk_fma_f32 v[12:13], v[110:111], v[32:33], v[12:13] op_sel_hi:[0,1,1]
	v_pk_fma_f32 v[14:15], v[110:111], v[40:41], v[14:15] op_sel_hi:[0,1,1]
	v_pk_fma_f32 v[8:9], v[110:111], v[48:49], v[8:9] op_sel_hi:[0,1,1]
	v_pk_fma_f32 v[10:11], v[112:113], v[20:21], v[10:11] op_sel_hi:[0,1,1]
	v_pk_fma_f32 v[12:13], v[112:113], v[28:29], v[12:13] op_sel_hi:[0,1,1]
	v_pk_fma_f32 v[14:15], v[112:113], v[36:37], v[14:15] op_sel_hi:[0,1,1]
	v_pk_fma_f32 v[8:9], v[112:113], v[44:45], v[8:9] op_sel_hi:[0,1,1]
	v_pk_fma_f32 v[10:11], v[114:115], v[26:27], v[10:11] op_sel_hi:[0,1,1]
	v_pk_fma_f32 v[12:13], v[114:115], v[34:35], v[12:13] op_sel_hi:[0,1,1]
	v_pk_fma_f32 v[14:15], v[114:115], v[42:43], v[14:15] op_sel_hi:[0,1,1]
	v_pk_fma_f32 v[8:9], v[114:115], v[50:51], v[8:9] op_sel_hi:[0,1,1]
	s_waitcnt vmcnt(4)
	ds_read_b128 v[20:23], v19
	ds_read_b128 v[24:27], v19 offset:4096
	ds_read_b128 v[28:31], v19 offset:8192
	ds_read_b128 v[32:35], v19 offset:12288
	ds_read_b128 v[36:39], v19 offset:16384
	ds_read_b128 v[40:43], v19 offset:20480
	ds_read_b128 v[44:47], v19 offset:24576
	ds_read_b128 v[48:51], v19 offset:28672
	s_waitcnt lgkmcnt(7)
	v_mov_b32_e32 v60, v20
	s_waitcnt lgkmcnt(6)
	v_mov_b32_e32 v61, v24
	s_waitcnt lgkmcnt(5)
	v_mov_b32_e32 v62, v28
	s_waitcnt lgkmcnt(4)
	v_mov_b32_e32 v63, v32
	s_waitcnt lgkmcnt(3)
	v_mov_b32_e32 v64, v36
	s_waitcnt lgkmcnt(2)
	v_mov_b32_e32 v65, v40
	s_waitcnt lgkmcnt(1)
	v_mov_b32_e32 v66, v44
	s_waitcnt lgkmcnt(0)
	v_mov_b32_e32 v67, v48
	v_mov_b32_e32 v24, v21
	v_mov_b32_e32 v32, v29
	v_mov_b32_e32 v40, v37
	v_mov_b32_e32 v48, v45
	v_mov_b32_e32 v20, v22
	v_mov_b32_e32 v21, v26
	v_mov_b32_e32 v28, v30
	v_mov_b32_e32 v29, v34
	v_mov_b32_e32 v36, v38
	v_mov_b32_e32 v37, v42
	v_mov_b32_e32 v44, v46
	v_mov_b32_e32 v45, v50
	v_mov_b32_e32 v26, v23
	v_mov_b32_e32 v34, v31
	v_mov_b32_e32 v42, v39
	v_mov_b32_e32 v50, v47
	v_add_u32_e32 v19, 16, v19
	v_pk_fma_f32 v[10:11], v[116:117], v[60:61], v[10:11] op_sel_hi:[0,1,1]
	v_pk_fma_f32 v[12:13], v[116:117], v[62:63], v[12:13] op_sel_hi:[0,1,1]
	v_pk_fma_f32 v[14:15], v[116:117], v[64:65], v[14:15] op_sel_hi:[0,1,1]
	v_pk_fma_f32 v[8:9], v[116:117], v[66:67], v[8:9] op_sel_hi:[0,1,1]
	v_pk_fma_f32 v[10:11], v[118:119], v[24:25], v[10:11] op_sel_hi:[0,1,1]
	v_pk_fma_f32 v[12:13], v[118:119], v[32:33], v[12:13] op_sel_hi:[0,1,1]
	v_pk_fma_f32 v[14:15], v[118:119], v[40:41], v[14:15] op_sel_hi:[0,1,1]
	v_pk_fma_f32 v[8:9], v[118:119], v[48:49], v[8:9] op_sel_hi:[0,1,1]
	v_pk_fma_f32 v[10:11], v[120:121], v[20:21], v[10:11] op_sel_hi:[0,1,1]
	v_pk_fma_f32 v[12:13], v[120:121], v[28:29], v[12:13] op_sel_hi:[0,1,1]
	v_pk_fma_f32 v[14:15], v[120:121], v[36:37], v[14:15] op_sel_hi:[0,1,1]
	v_pk_fma_f32 v[8:9], v[120:121], v[44:45], v[8:9] op_sel_hi:[0,1,1]
	v_pk_fma_f32 v[10:11], v[122:123], v[26:27], v[10:11] op_sel_hi:[0,1,1]
	v_pk_fma_f32 v[12:13], v[122:123], v[34:35], v[12:13] op_sel_hi:[0,1,1]
	v_pk_fma_f32 v[14:15], v[122:123], v[42:43], v[14:15] op_sel_hi:[0,1,1]
	v_pk_fma_f32 v[8:9], v[122:123], v[50:51], v[8:9] op_sel_hi:[0,1,1]
	s_waitcnt vmcnt(0)
	ds_read_b128 v[20:23], v19
	ds_read_b128 v[24:27], v19 offset:4096
	ds_read_b128 v[28:31], v19 offset:8192
	ds_read_b128 v[32:35], v19 offset:12288
	ds_read_b128 v[36:39], v19 offset:16384
	ds_read_b128 v[40:43], v19 offset:20480
	ds_read_b128 v[44:47], v19 offset:24576
	ds_read_b128 v[48:51], v19 offset:28672
	s_waitcnt lgkmcnt(7)
	v_mov_b32_e32 v60, v20
	s_waitcnt lgkmcnt(6)
	v_mov_b32_e32 v61, v24
	s_waitcnt lgkmcnt(5)
	v_mov_b32_e32 v62, v28
	s_waitcnt lgkmcnt(4)
	v_mov_b32_e32 v63, v32
	s_waitcnt lgkmcnt(3)
	v_mov_b32_e32 v64, v36
	s_waitcnt lgkmcnt(2)
	v_mov_b32_e32 v65, v40
	s_waitcnt lgkmcnt(1)
	v_mov_b32_e32 v66, v44
	s_waitcnt lgkmcnt(0)
	v_mov_b32_e32 v67, v48
	v_mov_b32_e32 v24, v21
	v_mov_b32_e32 v32, v29
	v_mov_b32_e32 v40, v37
	v_mov_b32_e32 v48, v45
	v_mov_b32_e32 v20, v22
	v_mov_b32_e32 v21, v26
	v_mov_b32_e32 v28, v30
	v_mov_b32_e32 v29, v34
	v_mov_b32_e32 v36, v38
	v_mov_b32_e32 v37, v42
	v_mov_b32_e32 v44, v46
	v_mov_b32_e32 v45, v50
	v_mov_b32_e32 v26, v23
	v_mov_b32_e32 v34, v31
	v_mov_b32_e32 v42, v39
	v_mov_b32_e32 v50, v47
	v_add_u32_e32 v19, 16, v19
	v_pk_fma_f32 v[10:11], v[140:141], v[60:61], v[10:11] op_sel_hi:[0,1,1]
	v_pk_fma_f32 v[12:13], v[140:141], v[62:63], v[12:13] op_sel_hi:[0,1,1]
	v_pk_fma_f32 v[14:15], v[140:141], v[64:65], v[14:15] op_sel_hi:[0,1,1]
	v_pk_fma_f32 v[8:9], v[140:141], v[66:67], v[8:9] op_sel_hi:[0,1,1]
	v_pk_fma_f32 v[10:11], v[142:143], v[24:25], v[10:11] op_sel_hi:[0,1,1]
	v_pk_fma_f32 v[12:13], v[142:143], v[32:33], v[12:13] op_sel_hi:[0,1,1]
	v_pk_fma_f32 v[14:15], v[142:143], v[40:41], v[14:15] op_sel_hi:[0,1,1]
	v_pk_fma_f32 v[8:9], v[142:143], v[48:49], v[8:9] op_sel_hi:[0,1,1]
	v_pk_fma_f32 v[10:11], v[144:145], v[20:21], v[10:11] op_sel_hi:[0,1,1]
	v_pk_fma_f32 v[12:13], v[144:145], v[28:29], v[12:13] op_sel_hi:[0,1,1]
	v_pk_fma_f32 v[14:15], v[144:145], v[36:37], v[14:15] op_sel_hi:[0,1,1]
	v_pk_fma_f32 v[8:9], v[144:145], v[44:45], v[8:9] op_sel_hi:[0,1,1]
	v_pk_fma_f32 v[10:11], v[146:147], v[26:27], v[10:11] op_sel_hi:[0,1,1]
	v_pk_fma_f32 v[12:13], v[146:147], v[34:35], v[12:13] op_sel_hi:[0,1,1]
	v_pk_fma_f32 v[14:15], v[146:147], v[42:43], v[14:15] op_sel_hi:[0,1,1]
	v_pk_fma_f32 v[8:9], v[146:147], v[50:51], v[8:9] op_sel_hi:[0,1,1]
	v_readlane_b32 s40, v254, 61
	s_mul_i32 s7, s0, 0x6000
	v_readlane_b32 s46, v255, 3
	s_mul_hi_i32 s6, s0, 0x6000
	v_readlane_b32 s47, v255, 4
	s_add_u32 s7, s46, s7
	s_addc_u32 s13, s47, s6
	s_add_u32 s6, s7, s2
	s_addc_u32 s7, s13, s3
	ds_write2st64_b32 v16, v10, v11 offset0:128 offset1:129
	ds_write2st64_b32 v16, v12, v13 offset0:130 offset1:131
	ds_write2st64_b32 v16, v14, v15 offset0:132 offset1:133
	ds_write2st64_b32 v16, v8, v9 offset0:134 offset1:135
	s_waitcnt lgkmcnt(0)
	s_barrier
	global_load_dword v19, v128, s[6:7]
	ds_read2st64_b32 v[6:7], v17 offset0:128 offset1:136
	ds_read2st64_b32 v[8:9], v17 offset0:144 offset1:152
	ds_read2st64_b32 v[10:11], v17 offset0:160 offset1:168
	ds_read2st64_b32 v[12:13], v17 offset0:176 offset1:184
	v_lshl_add_u64 v[14:15], s[0:1], 3, v[2:3]
	v_mov_b64_e32 v[20:21], s[58:59]
	s_waitcnt lgkmcnt(3)
	v_add_f32_e32 v6, 0, v6
	v_mad_u64_u32 v[20:21], s[0:1], v14, s84, v[20:21]
	v_add_f32_e32 v6, v6, v7
	s_load_dword s0, s[38:39], 0x0
	s_waitcnt lgkmcnt(0)
	v_add_f32_e32 v6, v6, v8
	v_add_f32_e32 v6, v6, v9
	v_add_f32_e32 v6, v6, v10
	v_add_f32_e32 v6, v6, v11
	v_mad_i32_i24 v21, v15, s84, v21
	v_add_f32_e32 v6, v6, v12
	v_lshl_add_u64 v[14:15], v[20:21], 0, s[2:3]
	s_add_i32 s12, s12, s0
	v_add_f32_e32 v6, v6, v13
	v_lshl_add_u64 v[14:15], v[14:15], 0, v[128:129]
	s_cmpk_gt_i32 s12, 0xbf
	v_readlane_b32 s41, v254, 62
	v_readlane_b32 s42, v254, 63
	v_readlane_b32 s43, v255, 0
	v_readlane_b32 s44, v255, 1
	v_readlane_b32 s45, v255, 2
	v_readlane_b32 s48, v255, 5
	v_readlane_b32 s49, v255, 6
	v_readlane_b32 s50, v255, 7
	v_readlane_b32 s51, v255, 8
	v_readlane_b32 s52, v255, 9
	v_readlane_b32 s53, v255, 10
	v_readlane_b32 s54, v255, 11
	v_readlane_b32 s55, v255, 12
	s_waitcnt vmcnt(0)
	v_add_f32_e32 v6, v6, v19
	global_store_dword v[14:15], v6, off
	s_barrier
	s_cbranch_scc0 .LBB0_417
